# hand-written selected-block attention loop: score masking via MFMA C bias, in-place accumulators, list prefetch
# speedup vs baseline: 1.0358x; 1.0358x over previous
; __device__ __forceinline__ float bf_lo(unsigned u) { return __uint_as_float(u << 16); }
; __device__ __forceinline__ void nsa_tile(const Ctx& C, int b, int g, int t0) {
;     ...
;         const int q16 = lane & 15, fq = lane >> 4, qi4 = q16 >> 2, head4 = g * 4 + (q16 & 3);
;         const bf16x8* kb = (const bf16x8*)(C.ws + WS_KSLC) + (size_t)bg * 512 * 256 + lane;
;         const bf16x8* vb = (const bf16x8*)(C.ws + WS_VSLC) + (size_t)bg * 512 * 256 + lane;
;         int nblk = 0;
; #pragma unroll
;         for (int c = 0; c < 4; ++c) {
;             const unsigned long long mk = __ballot(bmv[c] != 0u);
;             const int pos = nblk + (int)__builtin_amdgcn_mbcnt_hi((unsigned)(mk >> 32), __builtin_amdgcn_mbcnt_lo((unsigned)mk, 0u));
;             if (bmv[c] != 0u) list[pos] = (unsigned)(lane + 64 * c) | (bmv[c] << 16);
;             nblk += __builtin_popcountll(mk);
;         }
;         LDS_WAIT();
;         const int tq = t0 + qi4;
;         bf16x8 q16f[2][2]; float gs4[2];
; #pragma unroll
;         for (int sub = 0; sub < 2; ++sub) {
;             const size_t tok4 = (size_t)b * S_ + tq + 4 * sub;
;             const bf16_t* qp = P + tok4 * PP + PC_Q + head4 * 64;
;             q16f[sub][1] = scale_q(*(const u32x4*)(qp + 32 + 8 * fq), QS);
;             const u32x4 mv4 = *(const u32x4*)(qp + 8 * fq), pv4 = *(const u32x4*)(qp + 8 * ((fq ^ 1) & 1));
;             const float* rt = (const float*)(C.ws + WS_ROPE) + tok4 * 16;
;             const f32x4 ca = *(const f32x4*)rt, cb2 = *(const f32x4*)(rt + 4), sa = *(const f32x4*)(rt + 8), sb = *(const f32x4*)(rt + 12);
;             const float cs[8] = {ca.x, ca.y, ca.z, ca.w, cb2.x, cb2.y, cb2.z, cb2.w}, sn[8] = {sa.x, sa.y, sa.z, sa.w, sb.x, sb.y, sb.z, sb.w};
;             const float mv[8] = {bf_lo(mv4.x), bf_hi(mv4.x), bf_lo(mv4.y), bf_hi(mv4.y), bf_lo(mv4.z), bf_hi(mv4.z), bf_lo(mv4.w), bf_hi(mv4.w)};
;             const float pp[8] = {bf_lo(pv4.x), bf_hi(pv4.x), bf_lo(pv4.y), bf_hi(pv4.y), bf_lo(pv4.z), bf_hi(pv4.z), bf_lo(pv4.w), bf_hi(pv4.w)};
;             const bool roped = fq < 2; const float sg = (fq == 0) ? -1.f : 1.f; float o[8];
; #pragma unroll
;             for (int e = 0; e < 8; ++e) o[e] = (roped ? (mv[e] * cs[e] + sg * pp[e] * sn[e]) : mv[e]) * QS;
;             q16f[sub][0] = pack_p(o);
;             gs4[sub] = sigm(bf1(P[tok4 * PP + PC_NG + head4 * 3 + 1]));
.LBB0_809:
	s_or_b64 exec, exec, s[0:1]
	v_bfe_u32 v12, v224, 2, 2
	v_or_b32_e32 v211, s97, v12
	v_or_b32_e32 v10, s76, v211
	v_mov_b64_e32 v[2:3], s[86:87]
	v_mad_u64_u32 v[4:5], s[0:1], v10, s67, v[2:3]
	v_mov_b32_e32 v179, v1
	v_lshl_add_u64 v[6:7], v[4:5], 0, v[178:179]
	s_bcnt1_i32_b64 s2, vcc
	v_add_co_u32_e32 v6, vcc, 0x1000, v6
	s_waitcnt lgkmcnt(0)
	s_add_i32 s3, s3, s2
	s_nop 0
	v_addc_co_u32_e32 v7, vcc, 0, v7, vcc
	global_load_ushort v251, v[6:7], off offset:2562
	v_or_b32_e32 v6, 4, v10
	v_mad_u64_u32 v[2:3], s[0:1], v6, s67, v[2:3]
	v_lshl_add_u64 v[8:9], v[2:3], 0, v[178:179]
	v_add_co_u32_e32 v8, vcc, 0x1000, v8
	v_mov_b64_e32 v[246:247], 0x200
	s_nop 0
	v_addc_co_u32_e32 v9, vcc, 0, v9, vcc
	global_load_ushort v210, v[8:9], off offset:2562
	v_mov_b64_e32 v[216:217], 0xaff
	v_ashrrev_i32_e32 v245, 4, v224
	s_cmp_eq_u32 s3, 0
	v_lshlrev_b64 v[228:229], 4, v[224:225]
	v_lshlrev_b32_e32 v226, 1, v186
	s_cbranch_scc1 .LBB0_865
	v_lshlrev_b32_e32 v232, 3, v245
	v_ashrrev_i32_e32 v233, 31, v232
	v_mov_b32_e32 v227, v1
	v_lshl_add_u64 v[18:19], v[4:5], 0, v[226:227]
	v_lshlrev_b64 v[4:5], 1, v[232:233]
	v_lshl_add_u64 v[8:9], v[18:19], 0, v[4:5]
	global_load_dwordx4 v[14:17], v[8:9], off offset:3136
	v_bitop3_b32 v13, v232, 8, v232 bitop3:0xc
	v_mov_b32_e32 v11, v1
	v_lshlrev_b64 v[10:11], 6, v[10:11]
	v_lshl_add_u64 v[10:11], s[78:79], 0, v[10:11]
	s_lshl_b64 s[0:1], s[22:23], 4
	s_add_u32 s10, s90, s0
	s_addc_u32 s11, s91, s1
	s_add_u32 s4, s94, s0
	s_addc_u32 s5, s95, s1
	v_cmp_gt_u32_e64 s[0:1], 16, v224
	v_cmp_gt_i32_e32 vcc, 2, v245
	v_mov_b32_e32 v7, v1
	v_lshlrev_b64 v[6:7], 6, v[6:7]
	v_lshl_add_u64 v[6:7], s[78:79], 0, v[6:7]
	v_lshl_add_u64 v[234:235], s[4:5], 0, v[228:229]
	v_lshl_add_u64 v[230:231], s[10:11], 0, v[228:229]
	s_lshl_b32 s3, s3, 1
	s_mov_b32 s2, 4
	s_add_i32 s18, s3, -1
	s_waitcnt vmcnt(0)
	v_lshlrev_b32_e32 v20, 16, v14
	v_and_b32_e32 v21, 0xffff0000, v14
	v_lshlrev_b32_e32 v14, 16, v15
	v_and_b32_e32 v15, 0xffff0000, v15
	v_pk_mul_f32 v[14:15], v[14:15], s[38:39] op_sel_hi:[1,0]
	v_pk_mul_f32 v[20:21], v[20:21], s[38:39] op_sel_hi:[1,0]
	v_cvt_pk_bf16_f32 v99, v14, v15
	v_lshlrev_b32_e32 v14, 16, v16
	v_and_b32_e32 v15, 0xffff0000, v16
	v_pk_mul_f32 v[14:15], v[14:15], s[38:39] op_sel_hi:[1,0]
	v_cvt_pk_bf16_f32 v98, v20, v21
	v_cvt_pk_bf16_f32 v100, v14, v15
	v_lshlrev_b32_e32 v14, 16, v17
	v_and_b32_e32 v15, 0xffff0000, v17
	v_pk_mul_f32 v[14:15], v[14:15], s[38:39] op_sel_hi:[1,0]
	s_nop 0
	v_cvt_pk_bf16_f32 v101, v14, v15
	global_load_dwordx4 v[14:17], v[8:9], off offset:3072
	v_lshlrev_b32_e32 v8, 1, v13
	v_mov_b32_e32 v9, v1
	v_lshl_add_u64 v[18:19], v[18:19], 0, v[8:9]
	global_load_dwordx4 v[18:21], v[18:19], off offset:3072
	s_nop 0
	global_load_dwordx4 v[22:25], v[10:11], off offset:16
	global_load_dwordx4 v[26:29], v[10:11], off offset:48
	global_load_dwordx4 v[30:33], v[10:11], off
	global_load_dwordx4 v[34:37], v[10:11], off offset:32
	s_waitcnt vmcnt(5)
	v_lshlrev_b32_e32 v10, 16, v14
	v_lshlrev_b32_e32 v44, 16, v17
	v_and_b32_e32 v46, 0xffff0000, v17
	v_and_b32_e32 v14, 0xffff0000, v14
	s_waitcnt vmcnt(4)
	v_lshlrev_b32_e32 v11, 16, v18
	v_and_b32_e32 v13, 0xffff0000, v18
	v_lshlrev_b32_e32 v17, 16, v19
	v_and_b32_e32 v41, 0xffff0000, v19
	v_cndmask_b32_e64 v11, v11, -v11, s[0:1]
	s_waitcnt vmcnt(1)
	v_mov_b32_e32 v18, v30
	s_waitcnt vmcnt(0)
	v_mov_b32_e32 v19, v34
	v_pk_mul_f32 v[18:19], v[18:19], v[10:11]
	v_lshlrev_b32_e32 v38, 16, v15
	v_add_f32_e32 v11, v18, v19
	v_and_b32_e32 v40, 0xffff0000, v15
	v_cndmask_b32_e32 v10, v10, v11, vcc
	v_cndmask_b32_e64 v15, v13, -v13, s[0:1]
	v_mov_b32_e32 v34, v31
	v_mul_f32_e32 v18, 0x3e38aa3b, v10
	v_pk_mul_f32 v[10:11], v[34:35], v[14:15]
	v_cndmask_b32_e64 v39, v17, -v17, s[0:1]
	v_add_f32_e32 v10, v10, v11
	v_cndmask_b32_e32 v10, v14, v10, vcc
	v_mul_f32_e32 v13, 0x3e38aa3b, v10
	v_mov_b32_e32 v10, v32
	v_mov_b32_e32 v11, v36
	v_pk_mul_f32 v[10:11], v[10:11], v[38:39]
	v_cndmask_b32_e64 v41, v41, -v41, s[0:1]
	v_add_f32_e32 v10, v10, v11
	v_cndmask_b32_e32 v10, v38, v10, vcc
	v_mov_b32_e32 v36, v33
	v_mul_f32_e32 v14, 0x3e38aa3b, v10
	v_pk_mul_f32 v[10:11], v[36:37], v[40:41]
	v_lshlrev_b32_e32 v43, 16, v20
	v_add_f32_e32 v10, v10, v11
	v_cndmask_b32_e32 v10, v40, v10, vcc
	v_lshlrev_b32_e32 v42, 16, v16
	v_mul_f32_e32 v15, 0x3e38aa3b, v10
	v_cndmask_b32_e64 v43, v43, -v43, s[0:1]
	v_mov_b32_e32 v10, v22
	v_mov_b32_e32 v11, v26
	v_pk_mul_f32 v[10:11], v[10:11], v[42:43]
	v_and_b32_e32 v20, 0xffff0000, v20
	v_add_f32_e32 v10, v10, v11
	v_and_b32_e32 v16, 0xffff0000, v16
	v_cndmask_b32_e32 v10, v42, v10, vcc
	v_cndmask_b32_e64 v17, v20, -v20, s[0:1]
	v_mov_b32_e32 v26, v23
	v_mul_f32_e32 v19, 0x3e38aa3b, v10
	v_pk_mul_f32 v[10:11], v[26:27], v[16:17]
	v_lshlrev_b32_e32 v45, 16, v21
	v_add_f32_e32 v10, v10, v11
	v_cndmask_b32_e32 v10, v16, v10, vcc
	v_mul_f32_e32 v16, 0x3e38aa3b, v10
	v_cndmask_b32_e64 v45, v45, -v45, s[0:1]
	v_mov_b32_e32 v10, v24
	v_mov_b32_e32 v11, v28
	v_pk_mul_f32 v[10:11], v[10:11], v[44:45]
	v_and_b32_e32 v21, 0xffff0000, v21
	v_add_f32_e32 v10, v10, v11
	v_cndmask_b32_e32 v10, v44, v10, vcc
	v_cndmask_b32_e64 v47, v21, -v21, s[0:1]
	v_mov_b32_e32 v28, v25
	v_mul_f32_e32 v17, 0x3e38aa3b, v10
	v_pk_mul_f32 v[10:11], v[28:29], v[46:47]
	v_cvt_pk_bf16_f32 v103, v14, v15
	v_add_f32_e32 v10, v10, v11
	v_cndmask_b32_e32 v10, v46, v10, vcc
	v_mul_f32_e32 v10, 0x3e38aa3b, v10
	v_cvt_pk_bf16_f32 v105, v17, v10
	v_lshl_add_u64 v[10:11], v[2:3], 0, v[226:227]
	v_lshl_add_u64 v[14:15], v[10:11], 0, v[4:5]
	global_load_dwordx4 v[2:5], v[14:15], off offset:3136
	v_cvt_pk_bf16_f32 v104, v19, v16
	v_lshl_add_u64 v[8:9], v[10:11], 0, v[8:9]
	v_cvt_pk_bf16_f32 v102, v18, v13
	global_load_dwordx4 v[8:11], v[8:9], off offset:3072
	s_waitcnt vmcnt(1)
; #define LAS __attribute__((address_space(3)))
; __device__ __forceinline__ float bf_lo(unsigned u) { return __uint_as_float(u << 16); }
; __device__ __forceinline__ float bf_hi(unsigned u) { return __uint_as_float(u & 0xffff0000u); }
; __device__ __forceinline__ float bf1(bf16_t u) { return __uint_as_float(((unsigned)u) << 16); }
; __device__ __forceinline__ unsigned flash16_entry(int s, const LAS unsigned* list) {
;     const unsigned e = (unsigned)__builtin_amdgcn_readfirstlane((int)list[s >> 1]);
;     return (e & 0xffff0000u) | (2u * (e & 0xffffu) + (unsigned)(s & 1));
; }
; __device__ __forceinline__ void flash16_run(const bf16x8* kb, const bf16x8* vb, const bf16x8 (&qa)[2], const bf16x8 (&qb)[2], int nsteps, const LAS unsigned* list, int tq, int t0, int qi4, int fq, ...
;     if (nsteps <= 0) return;
;     bf16x8 kA[4], vA[4], kB[4], vB[4], kC[4], vC[4]; unsigned eA, eB, eC;
;     ...
;     F16_LOAD(0, kA, vA, eA); F16_LOAD(1, kB, vB, eB);
; __device__ __forceinline__ void nsa_tile(const Ctx& C, int b, int g, int t0) {
;     ...
;             const u32x4 mv4 = *(const u32x4*)(qp + 8 * fq), pv4 = *(const u32x4*)(qp + 8 * ((fq ^ 1) & 1));
;             const float* rt = (const float*)(C.ws + WS_ROPE) + tok4 * 16;
;             const f32x4 ca = *(const f32x4*)rt, cb2 = *(const f32x4*)(rt + 4), sa = *(const f32x4*)(rt + 8), sb = *(const f32x4*)(rt + 12);
;             const float cs[8] = {ca.x, ca.y, ca.z, ca.w, cb2.x, cb2.y, cb2.z, cb2.w}, sn[8] = {sa.x, sa.y, sa.z, sa.w, sb.x, sb.y, sb.z, sb.w};
;             const float mv[8] = {bf_lo(mv4.x), bf_hi(mv4.x), bf_lo(mv4.y), bf_hi(mv4.y), bf_lo(mv4.z), bf_hi(mv4.z), bf_lo(mv4.w), bf_hi(mv4.w)};
;             const float pp[8] = {bf_lo(pv4.x), bf_hi(pv4.x), bf_lo(pv4.y), bf_hi(pv4.y), bf_lo(pv4.z), bf_hi(pv4.z), bf_lo(pv4.w), bf_hi(pv4.w)};
;             const bool roped = fq < 2; const float sg = (fq == 0) ? -1.f : 1.f; float o[8];
; #pragma unroll
;             for (int e = 0; e < 8; ++e) o[e] = (roped ? (mv[e] * cs[e] + sg * pp[e] * sn[e]) : mv[e]) * QS;
;             q16f[sub][0] = pack_p(o);
;             gs4[sub] = sigm(bf1(P[tok4 * PP + PC_NG + head4 * 3 + 1]));
;         }
;         float ma = -1e30f, la = 0.f, mb = -1e30f, lb = 0.f; f32x4v Oa[4], Ob[4];
; #pragma unroll
;         for (int dt = 0; dt < 4; ++dt) { Oa[dt] = (f32x4v){0.f, 0.f, 0.f, 0.f}; Ob[dt] = (f32x4v){0.f, 0.f, 0.f, 0.f}; }
	v_lshlrev_b32_e32 v16, 16, v2
	v_and_b32_e32 v17, 0xffff0000, v2
	v_lshlrev_b32_e32 v2, 16, v3
	v_and_b32_e32 v3, 0xffff0000, v3
	v_pk_mul_f32 v[2:3], v[2:3], s[38:39] op_sel_hi:[1,0]
	v_pk_mul_f32 v[16:17], v[16:17], s[38:39] op_sel_hi:[1,0]
	v_cvt_pk_bf16_f32 v107, v2, v3
	v_lshlrev_b32_e32 v2, 16, v4
	v_and_b32_e32 v3, 0xffff0000, v4
	v_pk_mul_f32 v[2:3], v[2:3], s[38:39] op_sel_hi:[1,0]
	v_cvt_pk_bf16_f32 v106, v16, v17
	v_cvt_pk_bf16_f32 v108, v2, v3
	v_lshlrev_b32_e32 v2, 16, v5
	v_and_b32_e32 v3, 0xffff0000, v5
	v_pk_mul_f32 v[2:3], v[2:3], s[38:39] op_sel_hi:[1,0]
	s_waitcnt vmcnt(0)
	v_and_b32_e32 v13, 0xffff0000, v9
	v_cvt_pk_bf16_f32 v109, v2, v3
	global_load_dwordx4 v[2:5], v[14:15], off offset:3072
	s_nop 0
	global_load_dwordx4 v[14:17], v[6:7], off offset:16
	global_load_dwordx4 v[18:21], v[6:7], off offset:48
	global_load_dwordx4 v[22:25], v[6:7], off
	global_load_dwordx4 v[26:29], v[6:7], off offset:32
	v_lshlrev_b32_e32 v7, 16, v8
	v_lshlrev_b32_e32 v35, 16, v10
	v_and_b32_e32 v10, 0xffff0000, v10
	v_lshlrev_b32_e32 v37, 16, v11
	v_and_b32_e32 v11, 0xffff0000, v11
	v_cndmask_b32_e64 v7, v7, -v7, s[0:1]
	v_cndmask_b32_e64 v33, v13, -v13, s[0:1]
	v_cndmask_b32_e64 v35, v35, -v35, s[0:1]
	v_cndmask_b32_e64 v37, v37, -v37, s[0:1]
	v_cndmask_b32_e64 v39, v11, -v11, s[0:1]
	s_waitcnt vmcnt(4)
	v_lshlrev_b32_e32 v6, 16, v2
	v_lshlrev_b32_e32 v30, 16, v3
	v_and_b32_e32 v32, 0xffff0000, v3
	v_lshlrev_b32_e32 v36, 16, v5
	v_and_b32_e32 v38, 0xffff0000, v5
	v_and_b32_e32 v3, 0xffff0000, v8
	v_lshlrev_b32_e32 v5, 16, v9
	s_waitcnt vmcnt(1)
	v_mov_b32_e32 v8, v22
	s_waitcnt vmcnt(0)
	v_mov_b32_e32 v9, v26
	v_pk_mul_f32 v[8:9], v[8:9], v[6:7]
	v_and_b32_e32 v2, 0xffff0000, v2
	v_add_f32_e32 v7, v8, v9
	v_cndmask_b32_e32 v6, v6, v7, vcc
	v_cndmask_b32_e64 v3, v3, -v3, s[0:1]
	v_mov_b32_e32 v26, v23
	v_mul_f32_e32 v8, 0x3e38aa3b, v6
	v_pk_mul_f32 v[6:7], v[26:27], v[2:3]
	v_cndmask_b32_e64 v31, v5, -v5, s[0:1]
	v_add_f32_e32 v3, v6, v7
	v_cndmask_b32_e32 v2, v2, v3, vcc
	v_mul_f32_e32 v6, 0x3e38aa3b, v2
	v_mov_b32_e32 v2, v24
	v_mov_b32_e32 v3, v28
	v_pk_mul_f32 v[2:3], v[2:3], v[30:31]
	v_mov_b32_e32 v28, v25
	v_add_f32_e32 v2, v2, v3
	v_cndmask_b32_e32 v2, v30, v2, vcc
	v_mul_f32_e32 v7, 0x3e38aa3b, v2
	v_pk_mul_f32 v[2:3], v[28:29], v[32:33]
	v_lshlrev_b32_e32 v34, 16, v4
	v_add_f32_e32 v2, v2, v3
	v_cndmask_b32_e32 v2, v32, v2, vcc
	v_mul_f32_e32 v9, 0x3e38aa3b, v2
	v_mov_b32_e32 v2, v14
	v_mov_b32_e32 v3, v18
	v_pk_mul_f32 v[2:3], v[2:3], v[34:35]
	v_and_b32_e32 v4, 0xffff0000, v4
	v_add_f32_e32 v2, v2, v3
	v_cndmask_b32_e32 v2, v34, v2, vcc
	v_cndmask_b32_e64 v5, v10, -v10, s[0:1]
	v_mov_b32_e32 v18, v15
	v_mul_f32_e32 v13, 0x3e38aa3b, v2
	v_pk_mul_f32 v[2:3], v[18:19], v[4:5]
	v_cvt_pk_bf16_f32 v110, v8, v6
	v_add_f32_e32 v2, v2, v3
	v_cndmask_b32_e32 v2, v4, v2, vcc
	v_mul_f32_e32 v4, 0x3e38aa3b, v2
	v_mov_b32_e32 v2, v16
	v_mov_b32_e32 v3, v20
	v_pk_mul_f32 v[2:3], v[2:3], v[36:37]
	v_mov_b32_e32 v20, v17
	v_add_f32_e32 v2, v2, v3
	v_cndmask_b32_e32 v2, v36, v2, vcc
	v_mul_f32_e32 v5, 0x3e38aa3b, v2
	v_pk_mul_f32 v[2:3], v[20:21], v[38:39]
	v_mov_b32_e32 v6, s73
	v_add_f32_e32 v2, v2, v3
	v_cndmask_b32_e32 v2, v38, v2, vcc
	v_mul_f32_e32 v2, 0x3e38aa3b, v2
	v_cvt_pk_bf16_f32 v113, v5, v2
	v_cvt_pk_bf16_f32 v112, v13, v4
	v_cvt_pk_bf16_f32 v111, v7, v9
	v_lshlrev_b32_e64 v225, v12, 1
	v_or_b32_e32 v227, 4, v211
	v_mov_b32_e32 v18, v1
	v_mov_b32_e32 v19, v1
	v_mov_b32_e32 v20, v1
	v_mov_b32_e32 v21, v1
	v_mov_b32_e32 v22, v1
	v_mov_b32_e32 v23, v1
	v_mov_b32_e32 v24, v1
	v_mov_b32_e32 v25, v1
	v_mov_b32_e32 v26, v1
	v_mov_b32_e32 v27, v1
	v_mov_b32_e32 v28, v1
	v_mov_b32_e32 v29, v1
	v_mov_b32_e32 v30, v1
	v_mov_b32_e32 v31, v1
	v_mov_b32_e32 v32, v1
	v_mov_b32_e32 v33, v1
	v_mov_b32_e32 v34, v1
	v_mov_b32_e32 v35, v1
	v_mov_b32_e32 v36, v1
	v_mov_b32_e32 v37, v1
	v_mov_b32_e32 v38, v1
	v_mov_b32_e32 v39, v1
	v_mov_b32_e32 v40, v1
	v_mov_b32_e32 v41, v1
	v_mov_b32_e32 v42, v1
	v_mov_b32_e32 v43, v1
	v_mov_b32_e32 v44, v1
	v_mov_b32_e32 v45, v1
	v_mov_b32_e32 v46, v1
	v_mov_b32_e32 v47, v1
	v_mov_b32_e32 v48, v1
	v_mov_b32_e32 v49, v1
	v_mov_b32_e32 v236, v249
	v_mov_b32_e32 v237, v249
	v_mov_b32_e32 v60, v249
	v_mov_b32_e32 v61, v249
	v_mov_b32_e32 v240, 0
	v_mov_b32_e32 v241, 0
	v_mov_b32_e32 v238, 0
	v_mov_b32_e32 v239, 0
	v_mov_b32_e32 v55, s73
	ds_read_b32 v54, v55
	s_waitcnt lgkmcnt(0)
	v_readfirstlane_b32 s0, v54
	s_lshl_b32 s6, s0, 1
	s_and_b32 s6, s6, 0x1fffe
	s_and_b32 s0, s0, 0xffff0000
	s_or_b32 s16, s0, s6
	s_or_b32 s17, s16, 1
	s_lshl_b32 s6, s6, 12
	v_lshl_add_u64 v[56:57], v[230:231], 0, s[6:7]
	v_lshl_add_u64 v[58:59], v[234:235], 0, s[6:7]
	global_load_dwordx4 v[114:117], v[56:57], off
	global_load_dwordx4 v[118:121], v[56:57], off offset:1024
	global_load_dwordx4 v[122:125], v[56:57], off offset:2048
	global_load_dwordx4 v[126:129], v[56:57], off offset:3072
	global_load_dwordx4 v[130:133], v[58:59], off
	global_load_dwordx4 v[134:137], v[58:59], off offset:1024
	global_load_dwordx4 v[138:141], v[58:59], off offset:2048
	global_load_dwordx4 v[142:145], v[58:59], off offset:3072
	s_add_u32 s6, s6, 0x1000
	v_lshl_add_u64 v[56:57], v[230:231], 0, s[6:7]
	v_lshl_add_u64 v[58:59], v[234:235], 0, s[6:7]
	global_load_dwordx4 v[146:149], v[56:57], off
	global_load_dwordx4 v[150:153], v[56:57], off offset:1024
	global_load_dwordx4 v[154:157], v[56:57], off offset:2048
	global_load_dwordx4 v[158:161], v[56:57], off offset:3072
	global_load_dwordx4 v[162:165], v[58:59], off
	global_load_dwordx4 v[166:169], v[58:59], off offset:1024
	global_load_dwordx4 v[170:173], v[58:59], off offset:2048
	global_load_dwordx4 v[174:177], v[58:59], off offset:3072
	s_min_i32 s1, 2, s18
	s_lshl_b32 s1, s1, 1
	s_and_b32 s1, s1, -4
	s_add_i32 s1, s73, s1
	v_mov_b32_e32 v55, s1
	ds_read_b32 v54, v55
	s_mov_b32 s2, 0
; __device__ __forceinline__ float ex2(float x) { return __builtin_amdgcn_exp2f(x); }
; __device__ __forceinline__ bf16x8 pack_p(const float* p) { u32x4 w; w.x = cvt_pk_bf16(p[0], p[1]); w.y = cvt_pk_bf16(p[2], p[3]); w.z = cvt_pk_bf16(p[4], p[5]); w.w = cvt_pk_bf16(p[6], p[7]); return __builtin_bit_cast(bf16x8, w); }
; __device__ __forceinline__ void flash16_compute(bool domask, const bf16x8 (&kf)[4], const bf16x8 (&vf)[4], const bf16x8 (&q)[2], int x0, unsigned span, float& m, float& l, f32x4v (&O)[4]) {
;     f32x4v s0 = {0.f, 0.f, 0.f, 0.f}, s1 = {0.f, 0.f, 0.f, 0.f};
;     __builtin_amdgcn_s_setprio(1);
;     s0 = mfma16(kf[0], q[0], s0); s1 = mfma16(kf[2], q[0], s1);
;     s0 = mfma16(kf[1], q[1], s0); s1 = mfma16(kf[3], q[1], s1);
;     __builtin_amdgcn_s_setprio(0);
;     float sc[8] = {s0[0], s0[1], s0[2], s0[3], s1[0], s1[1], s1[2], s1[3]};
;     if (domask) {
; #pragma unroll
;         for (int j = 0; j < 8; ++j) sc[j] = ((unsigned)(x0 + j) <= span) ? sc[j] : -1e30f;
;     }
;     float mx = fmaxf(fmaxf(fmaxf(sc[0], sc[1]), fmaxf(sc[2], sc[3])), fmaxf(fmaxf(sc[4], sc[5]), fmaxf(sc[6], sc[7])));
;     mx = xq_max(mx);
;     const bool upd = mx > m + SM_THR;
;     if (__ballot(upd) != 0ull) {
;         const float mn = upd ? mx : m, alpha = ex2(m - mn); l *= alpha;
; #pragma unroll
;         for (int dt = 0; dt < 4; ++dt) O[dt] = O[dt] * alpha;
;         m = mn;
;     }
;     const float msub = (m < -1e29f) ? 0.f : m;
;     float p[8], ps = 0.f;
; #pragma unroll
;     for (int j = 0; j < 8; ++j) { p[j] = ex2(sc[j] - msub); ps += p[j]; }
;     l += ps;
;     const bf16x8 pb = pack_p(p);
;     __builtin_amdgcn_s_setprio(1);
; #pragma unroll
;     for (int dt = 0; dt < 4; ++dt) O[dt] = mfma16(vf[dt], pb, O[dt]);
;     __builtin_amdgcn_s_setprio(0);
; }
; __device__ __forceinline__ void flash16_run(const bf16x8* kb, const bf16x8* vb, const bf16x8 (&qa)[2], const bf16x8 (&qb)[2], int nsteps, const LAS unsigned* list, int tq, int t0, int qi4, int fq, ...
;     ...
;     F16_LOAD(0, kA, vA, eA); F16_LOAD(1, kB, vB, eB);
; #pragma unroll 1
;     for (int s = 0; s < nsteps; s += 3) {
;         F16_LOAD(s + 2, kC, vC, eC); F16_COMP(kA, vA, eA); if (s + 1 >= nsteps) break;
;         F16_LOAD(s + 3, kA, vA, eA); F16_COMP(kB, vB, eB); if (s + 2 >= nsteps) break;
;         F16_LOAD(s + 4, kB, vB, eB); F16_COMP(kC, vC, eC);
.Lsel_step_A:
	s_waitcnt lgkmcnt(0)
	v_readfirstlane_b32 s0, v54
	s_add_i32 s1, s2, 2
	s_min_i32 s1, s1, s18
	s_and_b32 s5, s1, 1
	s_lshl_b32 s6, s0, 1
	s_and_b32 s6, s6, 0x1fffe
	s_or_b32 s6, s6, s5
	s_and_b32 s0, s0, 0xffff0000
	s_or_b32 s19, s0, s6
	s_lshl_b32 s6, s6, 12
	v_lshl_add_u64 v[56:57], v[230:231], 0, s[6:7]
	v_lshl_add_u64 v[58:59], v[234:235], 0, s[6:7]
	s_add_i32 s1, s2, 3
	s_min_i32 s1, s1, s18
	s_lshl_b32 s1, s1, 1
	s_and_b32 s1, s1, -4
	s_add_i32 s1, s73, s1
	v_mov_b32_e32 v55, s1
	ds_read_b32 v54, v55
	global_load_dwordx4 v[178:181], v[56:57], off
	global_load_dwordx4 v[182:185], v[56:57], off offset:1024
	global_load_dwordx4 v[186:189], v[56:57], off offset:2048
	global_load_dwordx4 v[190:193], v[56:57], off offset:3072
	global_load_dwordx4 v[194:197], v[58:59], off
	global_load_dwordx4 v[198:201], v[58:59], off offset:1024
	global_load_dwordx4 v[202:205], v[58:59], off offset:2048
	global_load_dwordx4 v[206:209], v[58:59], off offset:3072
	s_and_b32 s10, s16, 0xffff
	s_lshl_b32 s10, s10, 5
	s_or_b32 s11, s10, 31
	s_cmp_le_u32 s11, s97
	s_cselect_b32 s22, 1, 0
	s_bfe_u32 s12, s16, 0x40010
	s_lshr_b32 s13, s16, 20
	s_waitcnt vmcnt(16)
	s_cmp_eq_u32 s12, 0
	s_cbranch_scc1 .Lsel_skip_Aa
	v_and_b32_e32 v14, s12, v225
	v_cmp_eq_u32_e32 vcc, 0, v14
	s_cmp_eq_u32 s22, 0
	s_cbranch_scc1 .Lsel_slow_Aa
	v_cndmask_b32_e32 v10, 0, v249, vcc
	v_cndmask_b32_e32 v11, 0, v249, vcc
	v_cndmask_b32_e32 v12, 0, v249, vcc
	v_cndmask_b32_e32 v13, 0, v249, vcc
	s_nop 1
	v_mfma_f32_16x16x32_bf16 v[2:5], v[114:117], v[102:105], v[10:13]
	v_mfma_f32_16x16x32_bf16 v[6:9], v[122:125], v[102:105], v[10:13]
.Lsel_qk2_Aa:
	v_mfma_f32_16x16x32_bf16 v[2:5], v[118:121], v[98:101], v[2:5]
	v_mfma_f32_16x16x32_bf16 v[6:9], v[126:129], v[98:101], v[6:9]
	s_nop 6
	v_max3_f32 v14, v2, v3, v4
	v_max3_f32 v14, v14, v5, v6
	v_max3_f32 v14, v14, v7, v8
	v_max_f32_e32 v14, v14, v9
	v_mov_b32_e32 v16, v14
	s_nop 1
	v_permlane16_swap_b32_e32 v14, v16
	v_max_f32_e32 v14, v14, v16
	v_mov_b32_e32 v16, v14
	s_nop 1
	v_permlane32_swap_b32_e32 v14, v16
	v_max_f32_e32 v14, v14, v16
	v_cmp_gt_f32_e32 vcc, v14, v60
	s_cbranch_vccnz .Lsel_upd_Aa
.Lsel_noupd_Aa:
	v_sub_f32_e32 v2, v2, v240
	v_sub_f32_e32 v3, v3, v240
	v_sub_f32_e32 v4, v4, v240
	v_sub_f32_e32 v5, v5, v240
	v_sub_f32_e32 v6, v6, v240
	v_sub_f32_e32 v7, v7, v240
	v_sub_f32_e32 v8, v8, v240
	v_sub_f32_e32 v9, v9, v240
	v_exp_f32_e32 v2, v2
	v_exp_f32_e32 v3, v3
	v_exp_f32_e32 v4, v4
	v_exp_f32_e32 v5, v5
	v_exp_f32_e32 v6, v6
	v_exp_f32_e32 v7, v7
	v_exp_f32_e32 v8, v8
	v_exp_f32_e32 v9, v9
	v_cvt_pk_bf16_f32 v50, v2, v3
	v_cvt_pk_bf16_f32 v51, v4, v5
	v_cvt_pk_bf16_f32 v52, v6, v7
	v_cvt_pk_bf16_f32 v53, v8, v9
	v_add_f32_e32 v14, v2, v3
	v_add_f32_e32 v14, v14, v4
	v_add_f32_e32 v14, v14, v5
	v_add_f32_e32 v14, v14, v6
	v_add_f32_e32 v14, v14, v7
	v_add_f32_e32 v14, v14, v8
	v_add_f32_e32 v14, v14, v9
	v_add_f32_e32 v238, v238, v14
	v_mfma_f32_16x16x32_bf16 v[34:37], v[130:133], v[50:53], v[34:37]
	v_mfma_f32_16x16x32_bf16 v[38:41], v[134:137], v[50:53], v[38:41]
	v_mfma_f32_16x16x32_bf16 v[42:45], v[138:141], v[50:53], v[42:45]
	v_mfma_f32_16x16x32_bf16 v[46:49], v[142:145], v[50:53], v[46:49]
.Lsel_skip_Aa:
	s_cmp_eq_u32 s13, 0
	s_cbranch_scc1 .Lsel_skip_Ab
	v_and_b32_e32 v14, s13, v225
	v_cmp_eq_u32_e32 vcc, 0, v14
	s_cmp_eq_u32 s22, 0
	s_cbranch_scc1 .Lsel_slow_Ab
	v_cndmask_b32_e32 v10, 0, v249, vcc
	v_cndmask_b32_e32 v11, 0, v249, vcc
	v_cndmask_b32_e32 v12, 0, v249, vcc
	v_cndmask_b32_e32 v13, 0, v249, vcc
	s_nop 1
	v_mfma_f32_16x16x32_bf16 v[2:5], v[114:117], v[110:113], v[10:13]
	v_mfma_f32_16x16x32_bf16 v[6:9], v[122:125], v[110:113], v[10:13]
.Lsel_qk2_Ab:
	v_mfma_f32_16x16x32_bf16 v[2:5], v[118:121], v[106:109], v[2:5]
	v_mfma_f32_16x16x32_bf16 v[6:9], v[126:129], v[106:109], v[6:9]
	s_nop 6
	v_max3_f32 v14, v2, v3, v4
	v_max3_f32 v14, v14, v5, v6
	v_max3_f32 v14, v14, v7, v8
	v_max_f32_e32 v14, v14, v9
	v_mov_b32_e32 v16, v14
	s_nop 1
	v_permlane16_swap_b32_e32 v14, v16
	v_max_f32_e32 v14, v14, v16
	v_mov_b32_e32 v16, v14
	s_nop 1
	v_permlane32_swap_b32_e32 v14, v16
	v_max_f32_e32 v14, v14, v16
	v_cmp_gt_f32_e32 vcc, v14, v61
	s_cbranch_vccnz .Lsel_upd_Ab
.Lsel_noupd_Ab:
	v_sub_f32_e32 v2, v2, v241
	v_sub_f32_e32 v3, v3, v241
	v_sub_f32_e32 v4, v4, v241
	v_sub_f32_e32 v5, v5, v241
	v_sub_f32_e32 v6, v6, v241
	v_sub_f32_e32 v7, v7, v241
	v_sub_f32_e32 v8, v8, v241
	v_sub_f32_e32 v9, v9, v241
	v_exp_f32_e32 v2, v2
	v_exp_f32_e32 v3, v3
	v_exp_f32_e32 v4, v4
	v_exp_f32_e32 v5, v5
	v_exp_f32_e32 v6, v6
	v_exp_f32_e32 v7, v7
	v_exp_f32_e32 v8, v8
	v_exp_f32_e32 v9, v9
	v_cvt_pk_bf16_f32 v50, v2, v3
	v_cvt_pk_bf16_f32 v51, v4, v5
	v_cvt_pk_bf16_f32 v52, v6, v7
	v_cvt_pk_bf16_f32 v53, v8, v9
	v_add_f32_e32 v14, v2, v3
	v_add_f32_e32 v14, v14, v4
	v_add_f32_e32 v14, v14, v5
	v_add_f32_e32 v14, v14, v6
	v_add_f32_e32 v14, v14, v7
	v_add_f32_e32 v14, v14, v8
	v_add_f32_e32 v14, v14, v9
	v_add_f32_e32 v239, v239, v14
	v_mfma_f32_16x16x32_bf16 v[18:21], v[130:133], v[50:53], v[18:21]
	v_mfma_f32_16x16x32_bf16 v[22:25], v[134:137], v[50:53], v[22:25]
	v_mfma_f32_16x16x32_bf16 v[26:29], v[138:141], v[50:53], v[26:29]
	v_mfma_f32_16x16x32_bf16 v[30:33], v[142:145], v[50:53], v[30:33]
; __device__ __forceinline__ float ex2(float x) { return __builtin_amdgcn_exp2f(x); }
; __device__ __forceinline__ bf16x8 pack_p(const float* p) { u32x4 w; w.x = cvt_pk_bf16(p[0], p[1]); w.y = cvt_pk_bf16(p[2], p[3]); w.z = cvt_pk_bf16(p[4], p[5]); w.w = cvt_pk_bf16(p[6], p[7]); return __builtin_bit_cast(bf16x8, w); }
; __device__ __forceinline__ void flash16_compute(bool domask, const bf16x8 (&kf)[4], const bf16x8 (&vf)[4], const bf16x8 (&q)[2], int x0, unsigned span, float& m, float& l, f32x4v (&O)[4]) {
;     f32x4v s0 = {0.f, 0.f, 0.f, 0.f}, s1 = {0.f, 0.f, 0.f, 0.f};
;     __builtin_amdgcn_s_setprio(1);
;     s0 = mfma16(kf[0], q[0], s0); s1 = mfma16(kf[2], q[0], s1);
;     s0 = mfma16(kf[1], q[1], s0); s1 = mfma16(kf[3], q[1], s1);
;     __builtin_amdgcn_s_setprio(0);
;     float sc[8] = {s0[0], s0[1], s0[2], s0[3], s1[0], s1[1], s1[2], s1[3]};
;     if (domask) {
; #pragma unroll
;         for (int j = 0; j < 8; ++j) sc[j] = ((unsigned)(x0 + j) <= span) ? sc[j] : -1e30f;
;     }
;     float mx = fmaxf(fmaxf(fmaxf(sc[0], sc[1]), fmaxf(sc[2], sc[3])), fmaxf(fmaxf(sc[4], sc[5]), fmaxf(sc[6], sc[7])));
;     mx = xq_max(mx);
;     const bool upd = mx > m + SM_THR;
;     if (__ballot(upd) != 0ull) {
;         const float mn = upd ? mx : m, alpha = ex2(m - mn); l *= alpha;
; #pragma unroll
;         for (int dt = 0; dt < 4; ++dt) O[dt] = O[dt] * alpha;
;         m = mn;
;     }
;     const float msub = (m < -1e29f) ? 0.f : m;
;     float p[8], ps = 0.f;
; #pragma unroll
;     for (int j = 0; j < 8; ++j) { p[j] = ex2(sc[j] - msub); ps += p[j]; }
;     l += ps;
;     const bf16x8 pb = pack_p(p);
;     __builtin_amdgcn_s_setprio(1);
; #pragma unroll
;     for (int dt = 0; dt < 4; ++dt) O[dt] = mfma16(vf[dt], pb, O[dt]);
;     __builtin_amdgcn_s_setprio(0);
; }
; __device__ __forceinline__ void flash16_run(const bf16x8* kb, const bf16x8* vb, const bf16x8 (&qa)[2], const bf16x8 (&qb)[2], int nsteps, const LAS unsigned* list, int tq, int t0, int qi4, int fq, ...
;     ...
;     F16_LOAD(0, kA, vA, eA); F16_LOAD(1, kB, vB, eB);
; #pragma unroll 1
;     for (int s = 0; s < nsteps; s += 3) {
;         F16_LOAD(s + 2, kC, vC, eC); F16_COMP(kA, vA, eA); if (s + 1 >= nsteps) break;
;         F16_LOAD(s + 3, kA, vA, eA); F16_COMP(kB, vB, eB); if (s + 2 >= nsteps) break;
;         F16_LOAD(s + 4, kB, vB, eB); F16_COMP(kC, vC, eC);
.Lsel_skip_Ab:
	s_add_i32 s2, s2, 1
	s_cmp_ge_u32 s2, s3
	s_cbranch_scc1 .Lsel_done
.Lsel_step_B:
	s_waitcnt lgkmcnt(0)
	v_readfirstlane_b32 s0, v54
	s_add_i32 s1, s2, 2
	s_min_i32 s1, s1, s18
	s_and_b32 s5, s1, 1
	s_lshl_b32 s6, s0, 1
	s_and_b32 s6, s6, 0x1fffe
	s_or_b32 s6, s6, s5
	s_and_b32 s0, s0, 0xffff0000
	s_or_b32 s16, s0, s6
	s_lshl_b32 s6, s6, 12
	v_lshl_add_u64 v[56:57], v[230:231], 0, s[6:7]
	v_lshl_add_u64 v[58:59], v[234:235], 0, s[6:7]
	s_add_i32 s1, s2, 3
	s_min_i32 s1, s1, s18
	s_lshl_b32 s1, s1, 1
	s_and_b32 s1, s1, -4
	s_add_i32 s1, s73, s1
	v_mov_b32_e32 v55, s1
	ds_read_b32 v54, v55
	global_load_dwordx4 v[114:117], v[56:57], off
	global_load_dwordx4 v[118:121], v[56:57], off offset:1024
	global_load_dwordx4 v[122:125], v[56:57], off offset:2048
	global_load_dwordx4 v[126:129], v[56:57], off offset:3072
	global_load_dwordx4 v[130:133], v[58:59], off
	global_load_dwordx4 v[134:137], v[58:59], off offset:1024
	global_load_dwordx4 v[138:141], v[58:59], off offset:2048
	global_load_dwordx4 v[142:145], v[58:59], off offset:3072
	s_and_b32 s10, s17, 0xffff
	s_lshl_b32 s10, s10, 5
	s_or_b32 s11, s10, 31
	s_cmp_le_u32 s11, s97
	s_cselect_b32 s22, 1, 0
	s_bfe_u32 s12, s17, 0x40010
	s_lshr_b32 s13, s17, 20
	s_waitcnt vmcnt(16)
	s_cmp_eq_u32 s12, 0
	s_cbranch_scc1 .Lsel_skip_Ba
	v_and_b32_e32 v14, s12, v225
	v_cmp_eq_u32_e32 vcc, 0, v14
	s_cmp_eq_u32 s22, 0
	s_cbranch_scc1 .Lsel_slow_Ba
	v_cndmask_b32_e32 v10, 0, v249, vcc
	v_cndmask_b32_e32 v11, 0, v249, vcc
	v_cndmask_b32_e32 v12, 0, v249, vcc
	v_cndmask_b32_e32 v13, 0, v249, vcc
	s_nop 1
	v_mfma_f32_16x16x32_bf16 v[2:5], v[146:149], v[102:105], v[10:13]
	v_mfma_f32_16x16x32_bf16 v[6:9], v[154:157], v[102:105], v[10:13]
.Lsel_qk2_Ba:
	v_mfma_f32_16x16x32_bf16 v[2:5], v[150:153], v[98:101], v[2:5]
	v_mfma_f32_16x16x32_bf16 v[6:9], v[158:161], v[98:101], v[6:9]
	s_nop 6
	v_max3_f32 v14, v2, v3, v4
	v_max3_f32 v14, v14, v5, v6
	v_max3_f32 v14, v14, v7, v8
	v_max_f32_e32 v14, v14, v9
	v_mov_b32_e32 v16, v14
	s_nop 1
	v_permlane16_swap_b32_e32 v14, v16
	v_max_f32_e32 v14, v14, v16
	v_mov_b32_e32 v16, v14
	s_nop 1
	v_permlane32_swap_b32_e32 v14, v16
	v_max_f32_e32 v14, v14, v16
	v_cmp_gt_f32_e32 vcc, v14, v60
	s_cbranch_vccnz .Lsel_upd_Ba
.Lsel_noupd_Ba:
	v_sub_f32_e32 v2, v2, v240
	v_sub_f32_e32 v3, v3, v240
	v_sub_f32_e32 v4, v4, v240
	v_sub_f32_e32 v5, v5, v240
	v_sub_f32_e32 v6, v6, v240
	v_sub_f32_e32 v7, v7, v240
	v_sub_f32_e32 v8, v8, v240
	v_sub_f32_e32 v9, v9, v240
	v_exp_f32_e32 v2, v2
	v_exp_f32_e32 v3, v3
	v_exp_f32_e32 v4, v4
	v_exp_f32_e32 v5, v5
	v_exp_f32_e32 v6, v6
	v_exp_f32_e32 v7, v7
	v_exp_f32_e32 v8, v8
	v_exp_f32_e32 v9, v9
	v_cvt_pk_bf16_f32 v50, v2, v3
	v_cvt_pk_bf16_f32 v51, v4, v5
	v_cvt_pk_bf16_f32 v52, v6, v7
	v_cvt_pk_bf16_f32 v53, v8, v9
	v_add_f32_e32 v14, v2, v3
	v_add_f32_e32 v14, v14, v4
	v_add_f32_e32 v14, v14, v5
	v_add_f32_e32 v14, v14, v6
	v_add_f32_e32 v14, v14, v7
	v_add_f32_e32 v14, v14, v8
	v_add_f32_e32 v14, v14, v9
	v_add_f32_e32 v238, v238, v14
	v_mfma_f32_16x16x32_bf16 v[34:37], v[162:165], v[50:53], v[34:37]
	v_mfma_f32_16x16x32_bf16 v[38:41], v[166:169], v[50:53], v[38:41]
	v_mfma_f32_16x16x32_bf16 v[42:45], v[170:173], v[50:53], v[42:45]
	v_mfma_f32_16x16x32_bf16 v[46:49], v[174:177], v[50:53], v[46:49]
.Lsel_skip_Ba:
	s_cmp_eq_u32 s13, 0
	s_cbranch_scc1 .Lsel_skip_Bb
	v_and_b32_e32 v14, s13, v225
	v_cmp_eq_u32_e32 vcc, 0, v14
	s_cmp_eq_u32 s22, 0
	s_cbranch_scc1 .Lsel_slow_Bb
	v_cndmask_b32_e32 v10, 0, v249, vcc
	v_cndmask_b32_e32 v11, 0, v249, vcc
	v_cndmask_b32_e32 v12, 0, v249, vcc
	v_cndmask_b32_e32 v13, 0, v249, vcc
	s_nop 1
	v_mfma_f32_16x16x32_bf16 v[2:5], v[146:149], v[110:113], v[10:13]
	v_mfma_f32_16x16x32_bf16 v[6:9], v[154:157], v[110:113], v[10:13]
.Lsel_qk2_Bb:
	v_mfma_f32_16x16x32_bf16 v[2:5], v[150:153], v[106:109], v[2:5]
	v_mfma_f32_16x16x32_bf16 v[6:9], v[158:161], v[106:109], v[6:9]
	s_nop 6
	v_max3_f32 v14, v2, v3, v4
	v_max3_f32 v14, v14, v5, v6
	v_max3_f32 v14, v14, v7, v8
	v_max_f32_e32 v14, v14, v9
	v_mov_b32_e32 v16, v14
	s_nop 1
	v_permlane16_swap_b32_e32 v14, v16
	v_max_f32_e32 v14, v14, v16
	v_mov_b32_e32 v16, v14
	s_nop 1
	v_permlane32_swap_b32_e32 v14, v16
	v_max_f32_e32 v14, v14, v16
	v_cmp_gt_f32_e32 vcc, v14, v61
	s_cbranch_vccnz .Lsel_upd_Bb
.Lsel_noupd_Bb:
	v_sub_f32_e32 v2, v2, v241
	v_sub_f32_e32 v3, v3, v241
	v_sub_f32_e32 v4, v4, v241
	v_sub_f32_e32 v5, v5, v241
	v_sub_f32_e32 v6, v6, v241
	v_sub_f32_e32 v7, v7, v241
	v_sub_f32_e32 v8, v8, v241
	v_sub_f32_e32 v9, v9, v241
	v_exp_f32_e32 v2, v2
	v_exp_f32_e32 v3, v3
	v_exp_f32_e32 v4, v4
	v_exp_f32_e32 v5, v5
	v_exp_f32_e32 v6, v6
	v_exp_f32_e32 v7, v7
	v_exp_f32_e32 v8, v8
	v_exp_f32_e32 v9, v9
	v_cvt_pk_bf16_f32 v50, v2, v3
	v_cvt_pk_bf16_f32 v51, v4, v5
	v_cvt_pk_bf16_f32 v52, v6, v7
	v_cvt_pk_bf16_f32 v53, v8, v9
	v_add_f32_e32 v14, v2, v3
	v_add_f32_e32 v14, v14, v4
	v_add_f32_e32 v14, v14, v5
	v_add_f32_e32 v14, v14, v6
	v_add_f32_e32 v14, v14, v7
	v_add_f32_e32 v14, v14, v8
	v_add_f32_e32 v14, v14, v9
	v_add_f32_e32 v239, v239, v14
	v_mfma_f32_16x16x32_bf16 v[18:21], v[162:165], v[50:53], v[18:21]
	v_mfma_f32_16x16x32_bf16 v[22:25], v[166:169], v[50:53], v[22:25]
	v_mfma_f32_16x16x32_bf16 v[26:29], v[170:173], v[50:53], v[26:29]
	v_mfma_f32_16x16x32_bf16 v[30:33], v[174:177], v[50:53], v[30:33]

; __device__ __forceinline__ float ex2(float x) { return __builtin_amdgcn_exp2f(x); }
; __device__ __forceinline__ bf16x8 pack_p(const float* p) { u32x4 w; w.x = cvt_pk_bf16(p[0], p[1]); w.y = cvt_pk_bf16(p[2], p[3]); w.z = cvt_pk_bf16(p[4], p[5]); w.w = cvt_pk_bf16(p[6], p[7]); return __builtin_bit_cast(bf16x8, w); }
; __device__ __forceinline__ void flash16_compute(bool domask, const bf16x8 (&kf)[4], const bf16x8 (&vf)[4], const bf16x8 (&q)[2], int x0, unsigned span, float& m, float& l, f32x4v (&O)[4]) {
;     f32x4v s0 = {0.f, 0.f, 0.f, 0.f}, s1 = {0.f, 0.f, 0.f, 0.f};
;     __builtin_amdgcn_s_setprio(1);
;     s0 = mfma16(kf[0], q[0], s0); s1 = mfma16(kf[2], q[0], s1);
;     s0 = mfma16(kf[1], q[1], s0); s1 = mfma16(kf[3], q[1], s1);
;     __builtin_amdgcn_s_setprio(0);
;     float sc[8] = {s0[0], s0[1], s0[2], s0[3], s1[0], s1[1], s1[2], s1[3]};
;     if (domask) {
; #pragma unroll
;         for (int j = 0; j < 8; ++j) sc[j] = ((unsigned)(x0 + j) <= span) ? sc[j] : -1e30f;
;     }
;     float mx = fmaxf(fmaxf(fmaxf(sc[0], sc[1]), fmaxf(sc[2], sc[3])), fmaxf(fmaxf(sc[4], sc[5]), fmaxf(sc[6], sc[7])));
;     mx = xq_max(mx);
;     const bool upd = mx > m + SM_THR;
;     if (__ballot(upd) != 0ull) {
;         const float mn = upd ? mx : m, alpha = ex2(m - mn); l *= alpha;
; #pragma unroll
;         for (int dt = 0; dt < 4; ++dt) O[dt] = O[dt] * alpha;
;         m = mn;
;     }
;     const float msub = (m < -1e29f) ? 0.f : m;
;     float p[8], ps = 0.f;
; #pragma unroll
;     for (int j = 0; j < 8; ++j) { p[j] = ex2(sc[j] - msub); ps += p[j]; }
;     l += ps;
;     const bf16x8 pb = pack_p(p);
;     __builtin_amdgcn_s_setprio(1);
; #pragma unroll
;     for (int dt = 0; dt < 4; ++dt) O[dt] = mfma16(vf[dt], pb, O[dt]);
;     __builtin_amdgcn_s_setprio(0);
; }
; __device__ __forceinline__ void flash16_run(const bf16x8* kb, const bf16x8* vb, const bf16x8 (&qa)[2], const bf16x8 (&qb)[2], int nsteps, const LAS unsigned* list, int tq, int t0, int qi4, int fq, ...
;     ...
;     F16_LOAD(0, kA, vA, eA); F16_LOAD(1, kB, vB, eB);
; #pragma unroll 1
;     for (int s = 0; s < nsteps; s += 3) {
;         F16_LOAD(s + 2, kC, vC, eC); F16_COMP(kA, vA, eA); if (s + 1 >= nsteps) break;
;         F16_LOAD(s + 3, kA, vA, eA); F16_COMP(kB, vB, eB); if (s + 2 >= nsteps) break;
;         F16_LOAD(s + 4, kB, vB, eB); F16_COMP(kC, vC, eC);
.Lsel_step_C:
	s_waitcnt lgkmcnt(0)
	v_readfirstlane_b32 s0, v54
	s_add_i32 s1, s2, 2
	s_min_i32 s1, s1, s18
	s_and_b32 s5, s1, 1
	s_lshl_b32 s6, s0, 1
	s_and_b32 s6, s6, 0x1fffe
	s_or_b32 s6, s6, s5
	s_and_b32 s0, s0, 0xffff0000
	s_or_b32 s17, s0, s6
	s_lshl_b32 s6, s6, 12
	v_lshl_add_u64 v[56:57], v[230:231], 0, s[6:7]
	v_lshl_add_u64 v[58:59], v[234:235], 0, s[6:7]
	s_add_i32 s1, s2, 3
	s_min_i32 s1, s1, s18
	s_lshl_b32 s1, s1, 1
	s_and_b32 s1, s1, -4
	s_add_i32 s1, s73, s1
	v_mov_b32_e32 v55, s1
	ds_read_b32 v54, v55
	global_load_dwordx4 v[146:149], v[56:57], off
	global_load_dwordx4 v[150:153], v[56:57], off offset:1024
	global_load_dwordx4 v[154:157], v[56:57], off offset:2048
	global_load_dwordx4 v[158:161], v[56:57], off offset:3072
	global_load_dwordx4 v[162:165], v[58:59], off
	global_load_dwordx4 v[166:169], v[58:59], off offset:1024
	global_load_dwordx4 v[170:173], v[58:59], off offset:2048
	global_load_dwordx4 v[174:177], v[58:59], off offset:3072
	s_and_b32 s10, s19, 0xffff
	s_lshl_b32 s10, s10, 5
	s_or_b32 s11, s10, 31
	s_cmp_le_u32 s11, s97
	s_cselect_b32 s22, 1, 0
	s_bfe_u32 s12, s19, 0x40010
	s_lshr_b32 s13, s19, 20
	s_waitcnt vmcnt(16)
	s_cmp_eq_u32 s12, 0
	s_cbranch_scc1 .Lsel_skip_Ca
	v_and_b32_e32 v14, s12, v225
	v_cmp_eq_u32_e32 vcc, 0, v14
	s_cmp_eq_u32 s22, 0
	s_cbranch_scc1 .Lsel_slow_Ca
	v_cndmask_b32_e32 v10, 0, v249, vcc
	v_cndmask_b32_e32 v11, 0, v249, vcc
	v_cndmask_b32_e32 v12, 0, v249, vcc
	v_cndmask_b32_e32 v13, 0, v249, vcc
	s_nop 1
	v_mfma_f32_16x16x32_bf16 v[2:5], v[178:181], v[102:105], v[10:13]
	v_mfma_f32_16x16x32_bf16 v[6:9], v[186:189], v[102:105], v[10:13]
.Lsel_qk2_Ca:
	v_mfma_f32_16x16x32_bf16 v[2:5], v[182:185], v[98:101], v[2:5]
	v_mfma_f32_16x16x32_bf16 v[6:9], v[190:193], v[98:101], v[6:9]
	s_nop 6
	v_max3_f32 v14, v2, v3, v4
	v_max3_f32 v14, v14, v5, v6
	v_max3_f32 v14, v14, v7, v8
	v_max_f32_e32 v14, v14, v9
	v_mov_b32_e32 v16, v14
	s_nop 1
	v_permlane16_swap_b32_e32 v14, v16
	v_max_f32_e32 v14, v14, v16
	v_mov_b32_e32 v16, v14
	s_nop 1
	v_permlane32_swap_b32_e32 v14, v16
	v_max_f32_e32 v14, v14, v16
	v_cmp_gt_f32_e32 vcc, v14, v60
	s_cbranch_vccnz .Lsel_upd_Ca
.Lsel_noupd_Ca:
	v_sub_f32_e32 v2, v2, v240
	v_sub_f32_e32 v3, v3, v240
	v_sub_f32_e32 v4, v4, v240
	v_sub_f32_e32 v5, v5, v240
	v_sub_f32_e32 v6, v6, v240
	v_sub_f32_e32 v7, v7, v240
	v_sub_f32_e32 v8, v8, v240
	v_sub_f32_e32 v9, v9, v240
	v_exp_f32_e32 v2, v2
	v_exp_f32_e32 v3, v3
	v_exp_f32_e32 v4, v4
	v_exp_f32_e32 v5, v5
	v_exp_f32_e32 v6, v6
	v_exp_f32_e32 v7, v7
	v_exp_f32_e32 v8, v8
	v_exp_f32_e32 v9, v9
	v_cvt_pk_bf16_f32 v50, v2, v3
	v_cvt_pk_bf16_f32 v51, v4, v5
	v_cvt_pk_bf16_f32 v52, v6, v7
	v_cvt_pk_bf16_f32 v53, v8, v9
	v_add_f32_e32 v14, v2, v3
	v_add_f32_e32 v14, v14, v4
	v_add_f32_e32 v14, v14, v5
	v_add_f32_e32 v14, v14, v6
	v_add_f32_e32 v14, v14, v7
	v_add_f32_e32 v14, v14, v8
	v_add_f32_e32 v14, v14, v9
	v_add_f32_e32 v238, v238, v14
	v_mfma_f32_16x16x32_bf16 v[34:37], v[194:197], v[50:53], v[34:37]
	v_mfma_f32_16x16x32_bf16 v[38:41], v[198:201], v[50:53], v[38:41]
	v_mfma_f32_16x16x32_bf16 v[42:45], v[202:205], v[50:53], v[42:45]
	v_mfma_f32_16x16x32_bf16 v[46:49], v[206:209], v[50:53], v[46:49]
.Lsel_skip_Ca:
	s_cmp_eq_u32 s13, 0
	s_cbranch_scc1 .Lsel_skip_Cb
	v_and_b32_e32 v14, s13, v225
	v_cmp_eq_u32_e32 vcc, 0, v14
	s_cmp_eq_u32 s22, 0
	s_cbranch_scc1 .Lsel_slow_Cb
	v_cndmask_b32_e32 v10, 0, v249, vcc
	v_cndmask_b32_e32 v11, 0, v249, vcc
	v_cndmask_b32_e32 v12, 0, v249, vcc
	v_cndmask_b32_e32 v13, 0, v249, vcc
	s_nop 1
	v_mfma_f32_16x16x32_bf16 v[2:5], v[178:181], v[110:113], v[10:13]
	v_mfma_f32_16x16x32_bf16 v[6:9], v[186:189], v[110:113], v[10:13]
.Lsel_qk2_Cb:
	v_mfma_f32_16x16x32_bf16 v[2:5], v[182:185], v[106:109], v[2:5]
	v_mfma_f32_16x16x32_bf16 v[6:9], v[190:193], v[106:109], v[6:9]
	s_nop 6
	v_max3_f32 v14, v2, v3, v4
	v_max3_f32 v14, v14, v5, v6
	v_max3_f32 v14, v14, v7, v8
	v_max_f32_e32 v14, v14, v9
	v_mov_b32_e32 v16, v14
	s_nop 1
	v_permlane16_swap_b32_e32 v14, v16
	v_max_f32_e32 v14, v14, v16
	v_mov_b32_e32 v16, v14
	s_nop 1
	v_permlane32_swap_b32_e32 v14, v16
	v_max_f32_e32 v14, v14, v16
	v_cmp_gt_f32_e32 vcc, v14, v61
	s_cbranch_vccnz .Lsel_upd_Cb
.Lsel_noupd_Cb:
	v_sub_f32_e32 v2, v2, v241
	v_sub_f32_e32 v3, v3, v241
	v_sub_f32_e32 v4, v4, v241
	v_sub_f32_e32 v5, v5, v241
	v_sub_f32_e32 v6, v6, v241
	v_sub_f32_e32 v7, v7, v241
	v_sub_f32_e32 v8, v8, v241
	v_sub_f32_e32 v9, v9, v241
	v_exp_f32_e32 v2, v2
	v_exp_f32_e32 v3, v3
	v_exp_f32_e32 v4, v4
	v_exp_f32_e32 v5, v5
	v_exp_f32_e32 v6, v6
	v_exp_f32_e32 v7, v7
	v_exp_f32_e32 v8, v8
	v_exp_f32_e32 v9, v9
	v_cvt_pk_bf16_f32 v50, v2, v3
	v_cvt_pk_bf16_f32 v51, v4, v5
	v_cvt_pk_bf16_f32 v52, v6, v7
	v_cvt_pk_bf16_f32 v53, v8, v9
	v_add_f32_e32 v14, v2, v3
	v_add_f32_e32 v14, v14, v4
	v_add_f32_e32 v14, v14, v5
	v_add_f32_e32 v14, v14, v6
	v_add_f32_e32 v14, v14, v7
	v_add_f32_e32 v14, v14, v8
	v_add_f32_e32 v14, v14, v9
	v_add_f32_e32 v239, v239, v14
	v_mfma_f32_16x16x32_bf16 v[18:21], v[194:197], v[50:53], v[18:21]
	v_mfma_f32_16x16x32_bf16 v[22:25], v[198:201], v[50:53], v[22:25]
	v_mfma_f32_16x16x32_bf16 v[26:29], v[202:205], v[50:53], v[26:29]
	v_mfma_f32_16x16x32_bf16 v[30:33], v[206:209], v[50:53], v[30:33]
; __device__ __forceinline__ float ex2(float x) { return __builtin_amdgcn_exp2f(x); }
; __device__ __forceinline__ f32x4v mfma16(bf16x8 a, bf16x8 b, f32x4v c) { return __builtin_amdgcn_mfma_f32_16x16x32_bf16(a, b, c, 0, 0, 0); }
; __device__ __forceinline__ float xq_max(float v) { const auto r = __builtin_amdgcn_permlane16_swap(__float_as_uint(v), __float_as_uint(v), false, false); return xhalf_max(fmaxf(__uint_as_float(r[0]), __uint_as_float(r[1]))); }
; #define F16_LOAD(S, KF, VF, E) do { const int sn_ = ((S) < nsteps) ? (S) : nsteps - 1; E = flash16_entry(sn_, list); const size_t go_ = (size_t)(E & 0xffffu) * 256; \
;         flash16_load(kb + go_, vb + go_, KF, VF); } while (0)
; __device__ __forceinline__ void flash16_compute(bool domask, const bf16x8 (&kf)[4], const bf16x8 (&vf)[4], const bf16x8 (&q)[2], int x0, unsigned span, float& m, float& l, f32x4v (&O)[4]) {
;     f32x4v s0 = {0.f, 0.f, 0.f, 0.f}, s1 = {0.f, 0.f, 0.f, 0.f};
;     __builtin_amdgcn_s_setprio(1);
;     s0 = mfma16(kf[0], q[0], s0); s1 = mfma16(kf[2], q[0], s1);
;     s0 = mfma16(kf[1], q[1], s0); s1 = mfma16(kf[3], q[1], s1);
;     __builtin_amdgcn_s_setprio(0);
;     float sc[8] = {s0[0], s0[1], s0[2], s0[3], s1[0], s1[1], s1[2], s1[3]};
;     if (domask) {
; #pragma unroll
;         for (int j = 0; j < 8; ++j) sc[j] = ((unsigned)(x0 + j) <= span) ? sc[j] : -1e30f;
;     }
;     float mx = fmaxf(fmaxf(fmaxf(sc[0], sc[1]), fmaxf(sc[2], sc[3])), fmaxf(fmaxf(sc[4], sc[5]), fmaxf(sc[6], sc[7])));
;     mx = xq_max(mx);
;     const bool upd = mx > m + SM_THR;
;     if (__ballot(upd) != 0ull) {
;         const float mn = upd ? mx : m, alpha = ex2(m - mn); l *= alpha;
; #pragma unroll
;         for (int dt = 0; dt < 4; ++dt) O[dt] = O[dt] * alpha;
;         m = mn;
;     }
;     const float msub = (m < -1e29f) ? 0.f : m;
; __device__ __forceinline__ void flash16_run(const bf16x8* kb, const bf16x8* vb, const bf16x8 (&qa)[2], const bf16x8 (&qb)[2], int nsteps, const LAS unsigned* list, int tq, int t0, int qi4, int fq, ...
;     ...
;     F16_LOAD(0, kA, vA, eA); F16_LOAD(1, kB, vB, eB);
; #pragma unroll 1
;     for (int s = 0; s < nsteps; s += 3) {
;         F16_LOAD(s + 2, kC, vC, eC); F16_COMP(kA, vA, eA); if (s + 1 >= nsteps) break;
;         F16_LOAD(s + 3, kA, vA, eA); F16_COMP(kB, vB, eB); if (s + 2 >= nsteps) break;
;         F16_LOAD(s + 4, kB, vB, eB); F16_COMP(kC, vC, eC);
.Lsel_skip_Cb:
	s_add_i32 s2, s2, 1
	s_cmp_lt_u32 s2, s3
	s_cbranch_scc1 .Lsel_step_A
.Lsel_done:
	s_waitcnt vmcnt(0) lgkmcnt(0)
	v_mov_b32_e32 v233, v213
	v_mov_b64_e32 v[234:235], v[214:215]
	s_branch .LBB0_866
.Lsel_slow_Aa:
	v_subrev_u32_e32 v16, s10, v211
	s_nop 0
	v_cndmask_b32_e64 v16, v16, -1, vcc
	v_cmp_lt_i32_e32 vcc, -1, v16
	v_max_i32_e32 v17, 0, v16
	s_nop 0
	v_cndmask_b32_e32 v16, 64, v232, vcc
	v_cmp_le_u32_e32 vcc, v16, v17
	s_nop 1
	v_cndmask_b32_e32 v2, v249, v1, vcc
	v_or_b32_e32 v15, 1, v16
	v_cmp_le_u32_e32 vcc, v15, v17
	s_nop 1
	v_cndmask_b32_e32 v3, v249, v1, vcc
	v_or_b32_e32 v15, 2, v16
	v_cmp_le_u32_e32 vcc, v15, v17
	s_nop 1
	v_cndmask_b32_e32 v4, v249, v1, vcc
	v_or_b32_e32 v15, 3, v16
	v_cmp_le_u32_e32 vcc, v15, v17
	s_nop 1
	v_cndmask_b32_e32 v5, v249, v1, vcc
	v_or_b32_e32 v15, 4, v16
	v_cmp_le_u32_e32 vcc, v15, v17
	s_nop 1
	v_cndmask_b32_e32 v6, v249, v1, vcc
	v_or_b32_e32 v15, 5, v16
	v_cmp_le_u32_e32 vcc, v15, v17
	s_nop 1
	v_cndmask_b32_e32 v7, v249, v1, vcc
	v_or_b32_e32 v15, 6, v16
	v_cmp_le_u32_e32 vcc, v15, v17
	s_nop 1
	v_cndmask_b32_e32 v8, v249, v1, vcc
	v_or_b32_e32 v15, 7, v16
	v_cmp_le_u32_e32 vcc, v15, v17
	s_nop 1
	v_cndmask_b32_e32 v9, v249, v1, vcc
	s_nop 1
	v_mfma_f32_16x16x32_bf16 v[2:5], v[114:117], v[102:105], v[2:5]
	v_mfma_f32_16x16x32_bf16 v[6:9], v[122:125], v[102:105], v[6:9]
	s_branch .Lsel_qk2_Aa
.Lsel_upd_Aa:
	s_nop 1
	v_cndmask_b32_e32 v16, v236, v14, vcc
	v_sub_f32_e32 v17, v236, v16
	v_exp_f32_e32 v17, v17
	v_mov_b32_e32 v236, v16
	v_add_f32_e32 v60, 0x41000000, v16
	v_mul_f32_e32 v238, v238, v17
	v_mul_f32_e32 v34, v34, v17
	v_mul_f32_e32 v35, v35, v17
	v_mul_f32_e32 v36, v36, v17
	v_mul_f32_e32 v37, v37, v17
	v_mul_f32_e32 v38, v38, v17
	v_mul_f32_e32 v39, v39, v17
	v_mul_f32_e32 v40, v40, v17
	v_mul_f32_e32 v41, v41, v17
	v_mul_f32_e32 v42, v42, v17
	v_mul_f32_e32 v43, v43, v17
	v_mul_f32_e32 v44, v44, v17
	v_mul_f32_e32 v45, v45, v17
	v_mul_f32_e32 v46, v46, v17
	v_mul_f32_e32 v47, v47, v17
	v_mul_f32_e32 v48, v48, v17
	v_mul_f32_e32 v49, v49, v17
	v_cmp_ngt_f32_e32 vcc, s66, v16
	s_nop 1
	v_cndmask_b32_e32 v240, 0, v16, vcc
	s_branch .Lsel_noupd_Aa
.Lsel_slow_Ab:
	v_subrev_u32_e32 v16, s10, v227
	s_nop 0
	v_cndmask_b32_e64 v16, v16, -1, vcc
	v_cmp_lt_i32_e32 vcc, -1, v16
	v_max_i32_e32 v17, 0, v16
	s_nop 0
	v_cndmask_b32_e32 v16, 64, v232, vcc
	v_cmp_le_u32_e32 vcc, v16, v17
	s_nop 1
	v_cndmask_b32_e32 v2, v249, v1, vcc
	v_or_b32_e32 v15, 1, v16
	v_cmp_le_u32_e32 vcc, v15, v17
	s_nop 1
	v_cndmask_b32_e32 v3, v249, v1, vcc
	v_or_b32_e32 v15, 2, v16
	v_cmp_le_u32_e32 vcc, v15, v17
	s_nop 1
	v_cndmask_b32_e32 v4, v249, v1, vcc
	v_or_b32_e32 v15, 3, v16
	v_cmp_le_u32_e32 vcc, v15, v17
	s_nop 1
	v_cndmask_b32_e32 v5, v249, v1, vcc
	v_or_b32_e32 v15, 4, v16
	v_cmp_le_u32_e32 vcc, v15, v17
	s_nop 1
	v_cndmask_b32_e32 v6, v249, v1, vcc
	v_or_b32_e32 v15, 5, v16
	v_cmp_le_u32_e32 vcc, v15, v17
	s_nop 1
	v_cndmask_b32_e32 v7, v249, v1, vcc
	v_or_b32_e32 v15, 6, v16
	v_cmp_le_u32_e32 vcc, v15, v17
	s_nop 1
	v_cndmask_b32_e32 v8, v249, v1, vcc
	v_or_b32_e32 v15, 7, v16
	v_cmp_le_u32_e32 vcc, v15, v17
	s_nop 1
	v_cndmask_b32_e32 v9, v249, v1, vcc
	s_nop 1
	v_mfma_f32_16x16x32_bf16 v[2:5], v[114:117], v[110:113], v[2:5]
	v_mfma_f32_16x16x32_bf16 v[6:9], v[122:125], v[110:113], v[6:9]
	s_branch .Lsel_qk2_Ab
.Lsel_upd_Ab:
	s_nop 1
	v_cndmask_b32_e32 v16, v237, v14, vcc
	v_sub_f32_e32 v17, v237, v16
	v_exp_f32_e32 v17, v17
	v_mov_b32_e32 v237, v16
	v_add_f32_e32 v61, 0x41000000, v16
	v_mul_f32_e32 v239, v239, v17
	v_mul_f32_e32 v18, v18, v17
	v_mul_f32_e32 v19, v19, v17
	v_mul_f32_e32 v20, v20, v17
	v_mul_f32_e32 v21, v21, v17
	v_mul_f32_e32 v22, v22, v17
	v_mul_f32_e32 v23, v23, v17
	v_mul_f32_e32 v24, v24, v17
	v_mul_f32_e32 v25, v25, v17
	v_mul_f32_e32 v26, v26, v17
	v_mul_f32_e32 v27, v27, v17
	v_mul_f32_e32 v28, v28, v17
	v_mul_f32_e32 v29, v29, v17
	v_mul_f32_e32 v30, v30, v17
	v_mul_f32_e32 v31, v31, v17
	v_mul_f32_e32 v32, v32, v17
	v_mul_f32_e32 v33, v33, v17
	v_cmp_ngt_f32_e32 vcc, s66, v16
	s_nop 1
	v_cndmask_b32_e32 v241, 0, v16, vcc
	s_branch .Lsel_noupd_Ab
.Lsel_slow_Ba:
	v_subrev_u32_e32 v16, s10, v211
	s_nop 0
	v_cndmask_b32_e64 v16, v16, -1, vcc
	v_cmp_lt_i32_e32 vcc, -1, v16
	v_max_i32_e32 v17, 0, v16
	s_nop 0
	v_cndmask_b32_e32 v16, 64, v232, vcc
	v_cmp_le_u32_e32 vcc, v16, v17
	s_nop 1
	v_cndmask_b32_e32 v2, v249, v1, vcc
	v_or_b32_e32 v15, 1, v16
	v_cmp_le_u32_e32 vcc, v15, v17
	s_nop 1
	v_cndmask_b32_e32 v3, v249, v1, vcc
	v_or_b32_e32 v15, 2, v16
	v_cmp_le_u32_e32 vcc, v15, v17
	s_nop 1
	v_cndmask_b32_e32 v4, v249, v1, vcc
	v_or_b32_e32 v15, 3, v16
	v_cmp_le_u32_e32 vcc, v15, v17
	s_nop 1
	v_cndmask_b32_e32 v5, v249, v1, vcc
	v_or_b32_e32 v15, 4, v16
	v_cmp_le_u32_e32 vcc, v15, v17
	s_nop 1
	v_cndmask_b32_e32 v6, v249, v1, vcc
	v_or_b32_e32 v15, 5, v16
	v_cmp_le_u32_e32 vcc, v15, v17
	s_nop 1
	v_cndmask_b32_e32 v7, v249, v1, vcc
	v_or_b32_e32 v15, 6, v16
	v_cmp_le_u32_e32 vcc, v15, v17
	s_nop 1
	v_cndmask_b32_e32 v8, v249, v1, vcc
	v_or_b32_e32 v15, 7, v16
	v_cmp_le_u32_e32 vcc, v15, v17
	s_nop 1
	v_cndmask_b32_e32 v9, v249, v1, vcc
	s_nop 1
	v_mfma_f32_16x16x32_bf16 v[2:5], v[146:149], v[102:105], v[2:5]
	v_mfma_f32_16x16x32_bf16 v[6:9], v[154:157], v[102:105], v[6:9]
	s_branch .Lsel_qk2_Ba

; __device__ __forceinline__ f32x4v mfma16(bf16x8 a, bf16x8 b, f32x4v c) { return __builtin_amdgcn_mfma_f32_16x16x32_bf16(a, b, c, 0, 0, 0); }
; __device__ __forceinline__ void flash16_compute(bool domask, const bf16x8 (&kf)[4], const bf16x8 (&vf)[4], const bf16x8 (&q)[2], int x0, unsigned span, float& m, float& l, f32x4v (&O)[4]) {
;     f32x4v s0 = {0.f, 0.f, 0.f, 0.f}, s1 = {0.f, 0.f, 0.f, 0.f};
;     __builtin_amdgcn_s_setprio(1);
;     s0 = mfma16(kf[0], q[0], s0); s1 = mfma16(kf[2], q[0], s1);
;     s0 = mfma16(kf[1], q[1], s0); s1 = mfma16(kf[3], q[1], s1);
;     __builtin_amdgcn_s_setprio(0);
;     float sc[8] = {s0[0], s0[1], s0[2], s0[3], s1[0], s1[1], s1[2], s1[3]};
;     if (domask) {
; #pragma unroll
;         for (int j = 0; j < 8; ++j) sc[j] = ((unsigned)(x0 + j) <= span) ? sc[j] : -1e30f;
.Lsel_slow_Bb:
	v_subrev_u32_e32 v16, s10, v227
	s_nop 0
	v_cndmask_b32_e64 v16, v16, -1, vcc
	v_cmp_lt_i32_e32 vcc, -1, v16
	v_max_i32_e32 v17, 0, v16
	s_nop 0
	v_cndmask_b32_e32 v16, 64, v232, vcc
	v_cmp_le_u32_e32 vcc, v16, v17
	s_nop 1
	v_cndmask_b32_e32 v2, v249, v1, vcc
	v_or_b32_e32 v15, 1, v16
	v_cmp_le_u32_e32 vcc, v15, v17
	s_nop 1
	v_cndmask_b32_e32 v3, v249, v1, vcc
	v_or_b32_e32 v15, 2, v16
	v_cmp_le_u32_e32 vcc, v15, v17
	s_nop 1
	v_cndmask_b32_e32 v4, v249, v1, vcc
	v_or_b32_e32 v15, 3, v16
	v_cmp_le_u32_e32 vcc, v15, v17
	s_nop 1
	v_cndmask_b32_e32 v5, v249, v1, vcc
	v_or_b32_e32 v15, 4, v16
	v_cmp_le_u32_e32 vcc, v15, v17
	s_nop 1
	v_cndmask_b32_e32 v6, v249, v1, vcc
	v_or_b32_e32 v15, 5, v16
	v_cmp_le_u32_e32 vcc, v15, v17
	s_nop 1
	v_cndmask_b32_e32 v7, v249, v1, vcc
	v_or_b32_e32 v15, 6, v16
	v_cmp_le_u32_e32 vcc, v15, v17
	s_nop 1
	v_cndmask_b32_e32 v8, v249, v1, vcc
	v_or_b32_e32 v15, 7, v16
	v_cmp_le_u32_e32 vcc, v15, v17
	s_nop 1
	v_cndmask_b32_e32 v9, v249, v1, vcc
	s_nop 1
	v_mfma_f32_16x16x32_bf16 v[2:5], v[146:149], v[110:113], v[2:5]
	v_mfma_f32_16x16x32_bf16 v[6:9], v[154:157], v[110:113], v[6:9]
	s_branch .Lsel_qk2_Bb

; __device__ __forceinline__ f32x4v mfma16(bf16x8 a, bf16x8 b, f32x4v c) { return __builtin_amdgcn_mfma_f32_16x16x32_bf16(a, b, c, 0, 0, 0); }
; __device__ __forceinline__ void flash16_compute(bool domask, const bf16x8 (&kf)[4], const bf16x8 (&vf)[4], const bf16x8 (&q)[2], int x0, unsigned span, float& m, float& l, f32x4v (&O)[4]) {
;     f32x4v s0 = {0.f, 0.f, 0.f, 0.f}, s1 = {0.f, 0.f, 0.f, 0.f};
;     __builtin_amdgcn_s_setprio(1);
;     s0 = mfma16(kf[0], q[0], s0); s1 = mfma16(kf[2], q[0], s1);
;     s0 = mfma16(kf[1], q[1], s0); s1 = mfma16(kf[3], q[1], s1);
;     __builtin_amdgcn_s_setprio(0);
;     float sc[8] = {s0[0], s0[1], s0[2], s0[3], s1[0], s1[1], s1[2], s1[3]};
;     if (domask) {
; #pragma unroll
;         for (int j = 0; j < 8; ++j) sc[j] = ((unsigned)(x0 + j) <= span) ? sc[j] : -1e30f;
.Lsel_slow_Ca:
	v_subrev_u32_e32 v16, s10, v211
	s_nop 0
	v_cndmask_b32_e64 v16, v16, -1, vcc
	v_cmp_lt_i32_e32 vcc, -1, v16
	v_max_i32_e32 v17, 0, v16
	s_nop 0
	v_cndmask_b32_e32 v16, 64, v232, vcc
	v_cmp_le_u32_e32 vcc, v16, v17
	s_nop 1
	v_cndmask_b32_e32 v2, v249, v1, vcc
	v_or_b32_e32 v15, 1, v16
	v_cmp_le_u32_e32 vcc, v15, v17
	s_nop 1
	v_cndmask_b32_e32 v3, v249, v1, vcc
	v_or_b32_e32 v15, 2, v16
	v_cmp_le_u32_e32 vcc, v15, v17
	s_nop 1
	v_cndmask_b32_e32 v4, v249, v1, vcc
	v_or_b32_e32 v15, 3, v16
	v_cmp_le_u32_e32 vcc, v15, v17
	s_nop 1
	v_cndmask_b32_e32 v5, v249, v1, vcc
	v_or_b32_e32 v15, 4, v16
	v_cmp_le_u32_e32 vcc, v15, v17
	s_nop 1
	v_cndmask_b32_e32 v6, v249, v1, vcc
	v_or_b32_e32 v15, 5, v16
	v_cmp_le_u32_e32 vcc, v15, v17
	s_nop 1
	v_cndmask_b32_e32 v7, v249, v1, vcc
	v_or_b32_e32 v15, 6, v16
	v_cmp_le_u32_e32 vcc, v15, v17
	s_nop 1
	v_cndmask_b32_e32 v8, v249, v1, vcc
	v_or_b32_e32 v15, 7, v16
	v_cmp_le_u32_e32 vcc, v15, v17
	s_nop 1
	v_cndmask_b32_e32 v9, v249, v1, vcc
	s_nop 1
	v_mfma_f32_16x16x32_bf16 v[2:5], v[178:181], v[102:105], v[2:5]
	v_mfma_f32_16x16x32_bf16 v[6:9], v[186:189], v[102:105], v[6:9]
	s_branch .Lsel_qk2_Ca

; __device__ __forceinline__ f32x4v mfma16(bf16x8 a, bf16x8 b, f32x4v c) { return __builtin_amdgcn_mfma_f32_16x16x32_bf16(a, b, c, 0, 0, 0); }
; __device__ __forceinline__ void flash16_compute(bool domask, const bf16x8 (&kf)[4], const bf16x8 (&vf)[4], const bf16x8 (&q)[2], int x0, unsigned span, float& m, float& l, f32x4v (&O)[4]) {
;     f32x4v s0 = {0.f, 0.f, 0.f, 0.f}, s1 = {0.f, 0.f, 0.f, 0.f};
;     __builtin_amdgcn_s_setprio(1);
;     s0 = mfma16(kf[0], q[0], s0); s1 = mfma16(kf[2], q[0], s1);
;     s0 = mfma16(kf[1], q[1], s0); s1 = mfma16(kf[3], q[1], s1);
;     __builtin_amdgcn_s_setprio(0);
;     float sc[8] = {s0[0], s0[1], s0[2], s0[3], s1[0], s1[1], s1[2], s1[3]};
;     if (domask) {
; #pragma unroll
;         for (int j = 0; j < 8; ++j) sc[j] = ((unsigned)(x0 + j) <= span) ? sc[j] : -1e30f;
.Lsel_slow_Cb:
	v_subrev_u32_e32 v16, s10, v227
	s_nop 0
	v_cndmask_b32_e64 v16, v16, -1, vcc
	v_cmp_lt_i32_e32 vcc, -1, v16
	v_max_i32_e32 v17, 0, v16
	s_nop 0
	v_cndmask_b32_e32 v16, 64, v232, vcc
	v_cmp_le_u32_e32 vcc, v16, v17
	s_nop 1
	v_cndmask_b32_e32 v2, v249, v1, vcc
	v_or_b32_e32 v15, 1, v16
	v_cmp_le_u32_e32 vcc, v15, v17
	s_nop 1
	v_cndmask_b32_e32 v3, v249, v1, vcc
	v_or_b32_e32 v15, 2, v16
	v_cmp_le_u32_e32 vcc, v15, v17
	s_nop 1
	v_cndmask_b32_e32 v4, v249, v1, vcc
	v_or_b32_e32 v15, 3, v16
	v_cmp_le_u32_e32 vcc, v15, v17
	s_nop 1
	v_cndmask_b32_e32 v5, v249, v1, vcc
	v_or_b32_e32 v15, 4, v16
	v_cmp_le_u32_e32 vcc, v15, v17
	s_nop 1
	v_cndmask_b32_e32 v6, v249, v1, vcc
	v_or_b32_e32 v15, 5, v16
	v_cmp_le_u32_e32 vcc, v15, v17
	s_nop 1
	v_cndmask_b32_e32 v7, v249, v1, vcc
	v_or_b32_e32 v15, 6, v16
	v_cmp_le_u32_e32 vcc, v15, v17
	s_nop 1
	v_cndmask_b32_e32 v8, v249, v1, vcc
	v_or_b32_e32 v15, 7, v16
	v_cmp_le_u32_e32 vcc, v15, v17
	s_nop 1
	v_cndmask_b32_e32 v9, v249, v1, vcc
	s_nop 1
	v_mfma_f32_16x16x32_bf16 v[2:5], v[178:181], v[110:113], v[2:5]
	v_mfma_f32_16x16x32_bf16 v[6:9], v[186:189], v[110:113], v[6:9]
	s_branch .Lsel_qk2_Cb
